# attention: K LDS-DMA after the second QK MFMA pair, V LDS-DMA after the third PV MFMA group
# speedup vs baseline: 1.0015x; 1.0015x over previous
; #define SBAR() __builtin_amdgcn_sched_barrier(0)
; #define VF_WAIT(N) do { asm volatile("s_waitcnt lgkmcnt(" #N ")" ::: "memory"); SBAR(); } while (0)
; #define A_WAITBAR(N) asm volatile("s_waitcnt vmcnt(" #N ") lgkmcnt(0) ; A256BAR\n\ts_barrier" ::: "memory")
; #define DMA_V(t, sl) do { const char* b_ = Vb + (size_t)(t) * TSTRIDE; const unsigned d_ = RFL(vdst + (sl) * 32768); glds16(b_ + voff[0], d_); glds16(b_ + voff[1], d_ + 1024); glds16(b_ + voff[2], d_ + 2048); glds16(b_ + voff[3], d_ + 3072); } while (0)
; __device__ __forceinline__ void pv8(f32x16* o, int vb, bf16x8 pa0, bf16x8 pa1, bf16x8 pa2, bf16x8 pa3) {
;   VFrag fa, fb; const int vb2 = vb + 16384;
;   vf_read<0>(fa, vb);
;   vf_read<1>(fb, vb);  VF_WAIT(8); vf_mma(o[0], fa, pa0, pa1, pa2, pa3); SBAR();
;   vf_read<2>(fa, vb);  VF_WAIT(8); vf_mma(o[1], fb, pa0, pa1, pa2, pa3); SBAR();
;   vf_read<3>(fb, vb);  VF_WAIT(8); vf_mma(o[2], fa, pa0, pa1, pa2, pa3); SBAR();
;   vf_read<0>(fa, vb2); VF_WAIT(8); vf_mma(o[3], fb, pa0, pa1, pa2, pa3); SBAR();
;   vf_read<1>(fb, vb2); VF_WAIT(8); vf_mma(o[4], fa, pa0, pa1, pa2, pa3); SBAR();
;   vf_read<2>(fa, vb2); VF_WAIT(8); vf_mma(o[5], fb, pa0, pa1, pa2, pa3); SBAR();
;   vf_read<3>(fb, vb2); VF_WAIT(8); vf_mma(o[6], fa, pa0, pa1, pa2, pa3); SBAR();
;   VF_WAIT(0); vf_mma(o[7], fb, pa0, pa1, pa2, pa3);
; }
; template <int mode> ...
;     ...
;     if (more) A_WAITBAR(6); else A_WAITBAR(0);
;     if (more) DMA_V(j + 2, s2);
;     pv8(o, vb0 + s0 * 32768, pa0, pa1, pa2, pa3);
;     if (more) A_WAITBAR(6); else A_WAITBAR(0);
.LBB0_363:
	v_lshl_add_u32 v220, s11, 15, v223
	ds_read_b64_tr_b16 v[144:145], v220 offset:0
	ds_read_b64_tr_b16 v[146:147], v220 offset:0x800
	ds_read_b64_tr_b16 v[148:149], v220 offset:0x1000
	ds_read_b64_tr_b16 v[150:151], v220 offset:0x1800
	ds_read_b64_tr_b16 v[152:153], v220 offset:0x2000
	ds_read_b64_tr_b16 v[154:155], v220 offset:0x2800
	ds_read_b64_tr_b16 v[156:157], v220 offset:0x3000
	ds_read_b64_tr_b16 v[158:159], v220 offset:0x3800
	ds_read_b64_tr_b16 v[194:195], v220 offset:0x200
	ds_read_b64_tr_b16 v[196:197], v220 offset:0xa00
	ds_read_b64_tr_b16 v[214:215], v220 offset:0x1200
	ds_read_b64_tr_b16 v[216:217], v220 offset:0x1a00
	ds_read_b64_tr_b16 v[228:229], v220 offset:0x2200
	ds_read_b64_tr_b16 v[230:231], v220 offset:0x2a00
	ds_read_b64_tr_b16 v[232:233], v220 offset:0x3200
	ds_read_b64_tr_b16 v[234:235], v220 offset:0x3a00
	s_waitcnt lgkmcnt(8)
	v_add_u32_e32 v221, 0x4000, v220
	v_mfma_f32_32x32x16_bf16 v[112:127], v[128:131], v[144:147], v[112:127]
	v_mfma_f32_32x32x16_bf16 v[112:127], v[132:135], v[148:151], v[112:127]
	v_mfma_f32_32x32x16_bf16 v[112:127], v[136:139], v[152:155], v[112:127]
	v_mfma_f32_32x32x16_bf16 v[112:127], v[140:143], v[156:159], v[112:127]
	ds_read_b64_tr_b16 v[144:145], v220 offset:0x400
	ds_read_b64_tr_b16 v[146:147], v220 offset:0xc00
	ds_read_b64_tr_b16 v[148:149], v220 offset:0x1400
	ds_read_b64_tr_b16 v[150:151], v220 offset:0x1c00
	ds_read_b64_tr_b16 v[152:153], v220 offset:0x2400
	ds_read_b64_tr_b16 v[154:155], v220 offset:0x2c00
	ds_read_b64_tr_b16 v[156:157], v220 offset:0x3400
	ds_read_b64_tr_b16 v[158:159], v220 offset:0x3c00
	s_waitcnt lgkmcnt(8)
	v_mfma_f32_32x32x16_bf16 v[96:111], v[128:131], v[194:197], v[96:111]
	v_mfma_f32_32x32x16_bf16 v[96:111], v[132:135], v[214:217], v[96:111]
	v_mfma_f32_32x32x16_bf16 v[96:111], v[136:139], v[228:231], v[96:111]
	v_mfma_f32_32x32x16_bf16 v[96:111], v[140:143], v[232:235], v[96:111]
	ds_read_b64_tr_b16 v[194:195], v220 offset:0x600
	ds_read_b64_tr_b16 v[196:197], v220 offset:0xe00
	ds_read_b64_tr_b16 v[214:215], v220 offset:0x1600
	ds_read_b64_tr_b16 v[216:217], v220 offset:0x1e00
	ds_read_b64_tr_b16 v[228:229], v220 offset:0x2600
	ds_read_b64_tr_b16 v[230:231], v220 offset:0x2e00
	ds_read_b64_tr_b16 v[232:233], v220 offset:0x3600
	ds_read_b64_tr_b16 v[234:235], v220 offset:0x3e00
	s_waitcnt lgkmcnt(8)
	v_mfma_f32_32x32x16_bf16 v[80:95], v[128:131], v[144:147], v[80:95]
	v_mfma_f32_32x32x16_bf16 v[80:95], v[132:135], v[148:151], v[80:95]
	v_mfma_f32_32x32x16_bf16 v[80:95], v[136:139], v[152:155], v[80:95]
	v_mfma_f32_32x32x16_bf16 v[80:95], v[140:143], v[156:159], v[80:95]
	ds_read_b64_tr_b16 v[144:145], v221 offset:0
	ds_read_b64_tr_b16 v[146:147], v221 offset:0x800
	ds_read_b64_tr_b16 v[148:149], v221 offset:0x1000
	ds_read_b64_tr_b16 v[150:151], v221 offset:0x1800
	ds_read_b64_tr_b16 v[152:153], v221 offset:0x2000
	ds_read_b64_tr_b16 v[154:155], v221 offset:0x2800
	ds_read_b64_tr_b16 v[156:157], v221 offset:0x3000
	ds_read_b64_tr_b16 v[158:159], v221 offset:0x3800
	s_cbranch_vccnz .Lp0_nodma
	s_lshl_b32 s12, s9, 15
	s_add_i32 s12, s12, s7
	s_mov_b32 s13, m0
	s_mov_b32 m0, s12
	s_nop 0
	global_load_lds_dwordx4 v204, s[38:39]
	s_add_i32 s24, s12, 0x400
	s_mov_b32 m0, s24
	s_nop 0
	global_load_lds_dwordx4 v206, s[38:39]
	s_add_i32 s24, s12, 0x800
	s_mov_b32 m0, s24
	s_nop 0
	global_load_lds_dwordx4 v208, s[38:39]
	s_add_i32 s24, s12, 0xc00
	s_mov_b32 m0, s24
	s_nop 0
	global_load_lds_dwordx4 v210, s[38:39]
	s_mov_b32 m0, s13
.Lp0_nodma:
	s_waitcnt lgkmcnt(8)
	v_mfma_f32_32x32x16_bf16 v[64:79], v[128:131], v[194:197], v[64:79]
	v_mfma_f32_32x32x16_bf16 v[64:79], v[132:135], v[214:217], v[64:79]
	v_mfma_f32_32x32x16_bf16 v[64:79], v[136:139], v[228:231], v[64:79]
	v_mfma_f32_32x32x16_bf16 v[64:79], v[140:143], v[232:235], v[64:79]
	ds_read_b64_tr_b16 v[194:195], v221 offset:0x200
	ds_read_b64_tr_b16 v[196:197], v221 offset:0xa00
	ds_read_b64_tr_b16 v[214:215], v221 offset:0x1200
	ds_read_b64_tr_b16 v[216:217], v221 offset:0x1a00
	ds_read_b64_tr_b16 v[228:229], v221 offset:0x2200
	ds_read_b64_tr_b16 v[230:231], v221 offset:0x2a00
	ds_read_b64_tr_b16 v[232:233], v221 offset:0x3200
	ds_read_b64_tr_b16 v[234:235], v221 offset:0x3a00
	s_waitcnt lgkmcnt(8)
	v_mfma_f32_32x32x16_bf16 v[48:63], v[128:131], v[144:147], v[48:63]
	v_mfma_f32_32x32x16_bf16 v[48:63], v[132:135], v[148:151], v[48:63]
	v_mfma_f32_32x32x16_bf16 v[48:63], v[136:139], v[152:155], v[48:63]
	v_mfma_f32_32x32x16_bf16 v[48:63], v[140:143], v[156:159], v[48:63]
	ds_read_b64_tr_b16 v[144:145], v221 offset:0x400
	ds_read_b64_tr_b16 v[146:147], v221 offset:0xc00
	ds_read_b64_tr_b16 v[148:149], v221 offset:0x1400
	ds_read_b64_tr_b16 v[150:151], v221 offset:0x1c00
	ds_read_b64_tr_b16 v[152:153], v221 offset:0x2400
	ds_read_b64_tr_b16 v[154:155], v221 offset:0x2c00
	ds_read_b64_tr_b16 v[156:157], v221 offset:0x3400
	ds_read_b64_tr_b16 v[158:159], v221 offset:0x3c00
	s_waitcnt lgkmcnt(8)
	v_mfma_f32_32x32x16_bf16 v[32:47], v[128:131], v[194:197], v[32:47]
	v_mfma_f32_32x32x16_bf16 v[32:47], v[132:135], v[214:217], v[32:47]
	v_mfma_f32_32x32x16_bf16 v[32:47], v[136:139], v[228:231], v[32:47]
	v_mfma_f32_32x32x16_bf16 v[32:47], v[140:143], v[232:235], v[32:47]
	ds_read_b64_tr_b16 v[194:195], v221 offset:0x600
	ds_read_b64_tr_b16 v[196:197], v221 offset:0xe00
	ds_read_b64_tr_b16 v[214:215], v221 offset:0x1600
	ds_read_b64_tr_b16 v[216:217], v221 offset:0x1e00
	ds_read_b64_tr_b16 v[228:229], v221 offset:0x2600
	ds_read_b64_tr_b16 v[230:231], v221 offset:0x2e00
	ds_read_b64_tr_b16 v[232:233], v221 offset:0x3600
	ds_read_b64_tr_b16 v[234:235], v221 offset:0x3e00
	s_waitcnt lgkmcnt(8)
	v_mfma_f32_32x32x16_bf16 v[16:31], v[128:131], v[144:147], v[16:31]
	v_mfma_f32_32x32x16_bf16 v[16:31], v[132:135], v[148:151], v[16:31]
	v_mfma_f32_32x32x16_bf16 v[16:31], v[136:139], v[152:155], v[16:31]
	v_mfma_f32_32x32x16_bf16 v[16:31], v[140:143], v[156:159], v[16:31]
	s_waitcnt lgkmcnt(0)
	v_mfma_f32_32x32x16_bf16 v[0:15], v[128:131], v[194:197], v[0:15]
	s_and_b64 vcc, exec, s[90:91]
	v_mfma_f32_32x32x16_bf16 v[0:15], v[132:135], v[214:217], v[0:15]
	v_mfma_f32_32x32x16_bf16 v[0:15], v[136:139], v[228:231], v[0:15]
	v_mfma_f32_32x32x16_bf16 v[0:15], v[140:143], v[232:235], v[0:15]
	s_cbranch_vccnz .Lm0_ybar0
	s_waitcnt vmcnt(6) lgkmcnt(0)
	s_barrier

; #define SBAR() __builtin_amdgcn_sched_barrier(0)
; #define VF_WAIT(N) do { asm volatile("s_waitcnt lgkmcnt(" #N ")" ::: "memory"); SBAR(); } while (0)
; #define A_WAITBAR(N) asm volatile("s_waitcnt vmcnt(" #N ") lgkmcnt(0) ; A256BAR\n\ts_barrier" ::: "memory")
; #define DMA_V(t, sl) do { const char* b_ = Vb + (size_t)(t) * TSTRIDE; const unsigned d_ = RFL(vdst + (sl) * 32768); glds16(b_ + voff[0], d_); glds16(b_ + voff[1], d_ + 1024); glds16(b_ + voff[2], d_ + 2048); glds16(b_ + voff[3], d_ + 3072); } while (0)
; __device__ __forceinline__ void pv8(f32x16* o, int vb, bf16x8 pa0, bf16x8 pa1, bf16x8 pa2, bf16x8 pa3) {
;   VFrag fa, fb; const int vb2 = vb + 16384;
;   vf_read<0>(fa, vb);
;   vf_read<1>(fb, vb);  VF_WAIT(8); vf_mma(o[0], fa, pa0, pa1, pa2, pa3); SBAR();
;   vf_read<2>(fa, vb);  VF_WAIT(8); vf_mma(o[1], fb, pa0, pa1, pa2, pa3); SBAR();
;   vf_read<3>(fb, vb);  VF_WAIT(8); vf_mma(o[2], fa, pa0, pa1, pa2, pa3); SBAR();
;   vf_read<0>(fa, vb2); VF_WAIT(8); vf_mma(o[3], fb, pa0, pa1, pa2, pa3); SBAR();
;   vf_read<1>(fb, vb2); VF_WAIT(8); vf_mma(o[4], fa, pa0, pa1, pa2, pa3); SBAR();
;   vf_read<2>(fa, vb2); VF_WAIT(8); vf_mma(o[5], fb, pa0, pa1, pa2, pa3); SBAR();
;   vf_read<3>(fb, vb2); VF_WAIT(8); vf_mma(o[6], fa, pa0, pa1, pa2, pa3); SBAR();
;   VF_WAIT(0); vf_mma(o[7], fb, pa0, pa1, pa2, pa3);
; }
; template <int mode> ...
;     ...
;     if (more) A_WAITBAR(6); else A_WAITBAR(0);
;     if (more) DMA_V(j + 2, s2);
;     pv8(o, vb0 + s0 * 32768, pa0, pa1, pa2, pa3);
;     if (more) A_WAITBAR(6); else A_WAITBAR(0);
.LBB0_396:
	v_lshl_add_u32 v231, s10, 15, v226
	ds_read_b64_tr_b16 v[144:145], v231 offset:0
	ds_read_b64_tr_b16 v[146:147], v231 offset:0x800
	ds_read_b64_tr_b16 v[148:149], v231 offset:0x1000
	ds_read_b64_tr_b16 v[150:151], v231 offset:0x1800
	ds_read_b64_tr_b16 v[152:153], v231 offset:0x2000
	ds_read_b64_tr_b16 v[154:155], v231 offset:0x2800
	ds_read_b64_tr_b16 v[156:157], v231 offset:0x3000
	ds_read_b64_tr_b16 v[158:159], v231 offset:0x3800
	ds_read_b64_tr_b16 v[194:195], v231 offset:0x200
	ds_read_b64_tr_b16 v[196:197], v231 offset:0xa00
	ds_read_b64_tr_b16 v[214:215], v231 offset:0x1200
	ds_read_b64_tr_b16 v[216:217], v231 offset:0x1a00
	ds_read_b64_tr_b16 v[220:221], v231 offset:0x2200
	ds_read_b64_tr_b16 v[222:223], v231 offset:0x2a00
	ds_read_b64_tr_b16 v[232:233], v231 offset:0x3200
	ds_read_b64_tr_b16 v[234:235], v231 offset:0x3a00
	s_waitcnt lgkmcnt(8)
	v_add_u32_e32 v236, 0x4000, v231
	v_mfma_f32_32x32x16_bf16 v[16:31], v[128:131], v[144:147], v[16:31]
	v_mfma_f32_32x32x16_bf16 v[16:31], v[132:135], v[148:151], v[16:31]
	v_mfma_f32_32x32x16_bf16 v[16:31], v[136:139], v[152:155], v[16:31]
	v_mfma_f32_32x32x16_bf16 v[16:31], v[140:143], v[156:159], v[16:31]
	ds_read_b64_tr_b16 v[144:145], v231 offset:0x400
	ds_read_b64_tr_b16 v[146:147], v231 offset:0xc00
	ds_read_b64_tr_b16 v[148:149], v231 offset:0x1400
	ds_read_b64_tr_b16 v[150:151], v231 offset:0x1c00
	ds_read_b64_tr_b16 v[152:153], v231 offset:0x2400
	ds_read_b64_tr_b16 v[154:155], v231 offset:0x2c00
	ds_read_b64_tr_b16 v[156:157], v231 offset:0x3400
	ds_read_b64_tr_b16 v[158:159], v231 offset:0x3c00
	s_waitcnt lgkmcnt(8)
	v_mfma_f32_32x32x16_bf16 v[32:47], v[128:131], v[194:197], v[32:47]
	v_mfma_f32_32x32x16_bf16 v[32:47], v[132:135], v[214:217], v[32:47]
	v_mfma_f32_32x32x16_bf16 v[32:47], v[136:139], v[220:223], v[32:47]
	v_mfma_f32_32x32x16_bf16 v[32:47], v[140:143], v[232:235], v[32:47]
	ds_read_b64_tr_b16 v[194:195], v231 offset:0x600
	ds_read_b64_tr_b16 v[196:197], v231 offset:0xe00
	ds_read_b64_tr_b16 v[214:215], v231 offset:0x1600
	ds_read_b64_tr_b16 v[216:217], v231 offset:0x1e00
	ds_read_b64_tr_b16 v[220:221], v231 offset:0x2600
	ds_read_b64_tr_b16 v[222:223], v231 offset:0x2e00
	ds_read_b64_tr_b16 v[232:233], v231 offset:0x3600
	ds_read_b64_tr_b16 v[234:235], v231 offset:0x3e00
	s_waitcnt lgkmcnt(8)
	v_mfma_f32_32x32x16_bf16 v[96:111], v[128:131], v[144:147], v[96:111]
	v_mfma_f32_32x32x16_bf16 v[96:111], v[132:135], v[148:151], v[96:111]
	v_mfma_f32_32x32x16_bf16 v[96:111], v[136:139], v[152:155], v[96:111]
	v_mfma_f32_32x32x16_bf16 v[96:111], v[140:143], v[156:159], v[96:111]
	ds_read_b64_tr_b16 v[144:145], v236 offset:0
	ds_read_b64_tr_b16 v[146:147], v236 offset:0x800
	ds_read_b64_tr_b16 v[148:149], v236 offset:0x1000
	ds_read_b64_tr_b16 v[150:151], v236 offset:0x1800
	ds_read_b64_tr_b16 v[152:153], v236 offset:0x2000
	ds_read_b64_tr_b16 v[154:155], v236 offset:0x2800
	ds_read_b64_tr_b16 v[156:157], v236 offset:0x3000
	ds_read_b64_tr_b16 v[158:159], v236 offset:0x3800
	s_cbranch_vccnz .Lp1_nodma
	s_lshl_b32 s11, s7, 15
	s_add_i32 s11, s11, s5
	s_mov_b32 s12, m0
	s_mov_b32 m0, s11
	s_nop 0
	global_load_lds_dwordx4 v204, s[60:61]
	s_add_i32 s13, s11, 0x400
	s_mov_b32 m0, s13
	s_nop 0
	global_load_lds_dwordx4 v206, s[60:61]
	s_add_i32 s13, s11, 0x800
	s_mov_b32 m0, s13
	s_nop 0
	global_load_lds_dwordx4 v208, s[60:61]
	s_add_i32 s13, s11, 0xc00
	s_mov_b32 m0, s13
	s_nop 0
	global_load_lds_dwordx4 v210, s[60:61]
	s_mov_b32 m0, s12
.Lp1_nodma:
	s_waitcnt lgkmcnt(8)
	v_mfma_f32_32x32x16_bf16 v[112:127], v[128:131], v[194:197], v[112:127]
	v_mfma_f32_32x32x16_bf16 v[112:127], v[132:135], v[214:217], v[112:127]
	v_mfma_f32_32x32x16_bf16 v[112:127], v[136:139], v[220:223], v[112:127]
	v_mfma_f32_32x32x16_bf16 v[112:127], v[140:143], v[232:235], v[112:127]
	ds_read_b64_tr_b16 v[194:195], v236 offset:0x200
	ds_read_b64_tr_b16 v[196:197], v236 offset:0xa00
	ds_read_b64_tr_b16 v[214:215], v236 offset:0x1200
	ds_read_b64_tr_b16 v[216:217], v236 offset:0x1a00
	ds_read_b64_tr_b16 v[220:221], v236 offset:0x2200
	ds_read_b64_tr_b16 v[222:223], v236 offset:0x2a00
	ds_read_b64_tr_b16 v[232:233], v236 offset:0x3200
	ds_read_b64_tr_b16 v[234:235], v236 offset:0x3a00
	s_waitcnt lgkmcnt(8)
	v_mfma_f32_32x32x16_bf16 v[64:79], v[128:131], v[144:147], v[64:79]
	v_mfma_f32_32x32x16_bf16 v[64:79], v[132:135], v[148:151], v[64:79]
	v_mfma_f32_32x32x16_bf16 v[64:79], v[136:139], v[152:155], v[64:79]
	v_mfma_f32_32x32x16_bf16 v[64:79], v[140:143], v[156:159], v[64:79]
	ds_read_b64_tr_b16 v[144:145], v236 offset:0x400
	ds_read_b64_tr_b16 v[146:147], v236 offset:0xc00
	ds_read_b64_tr_b16 v[148:149], v236 offset:0x1400
	ds_read_b64_tr_b16 v[150:151], v236 offset:0x1c00
	ds_read_b64_tr_b16 v[152:153], v236 offset:0x2400
	ds_read_b64_tr_b16 v[154:155], v236 offset:0x2c00
	ds_read_b64_tr_b16 v[156:157], v236 offset:0x3400
	ds_read_b64_tr_b16 v[158:159], v236 offset:0x3c00
	s_waitcnt lgkmcnt(8)
	v_mfma_f32_32x32x16_bf16 v[48:63], v[128:131], v[194:197], v[48:63]
	v_mfma_f32_32x32x16_bf16 v[48:63], v[132:135], v[214:217], v[48:63]
	v_mfma_f32_32x32x16_bf16 v[48:63], v[136:139], v[220:223], v[48:63]
	v_mfma_f32_32x32x16_bf16 v[48:63], v[140:143], v[232:235], v[48:63]
	ds_read_b64_tr_b16 v[194:195], v236 offset:0x600
	ds_read_b64_tr_b16 v[196:197], v236 offset:0xe00
	ds_read_b64_tr_b16 v[214:215], v236 offset:0x1600
	ds_read_b64_tr_b16 v[216:217], v236 offset:0x1e00
	ds_read_b64_tr_b16 v[220:221], v236 offset:0x2600
	ds_read_b64_tr_b16 v[222:223], v236 offset:0x2e00
	ds_read_b64_tr_b16 v[232:233], v236 offset:0x3600
	ds_read_b64_tr_b16 v[234:235], v236 offset:0x3e00
	s_waitcnt lgkmcnt(8)
	v_mfma_f32_32x32x16_bf16 v[0:15], v[128:131], v[144:147], v[0:15]
	v_mfma_f32_32x32x16_bf16 v[0:15], v[132:135], v[148:151], v[0:15]
	v_mfma_f32_32x32x16_bf16 v[0:15], v[136:139], v[152:155], v[0:15]
	v_mfma_f32_32x32x16_bf16 v[0:15], v[140:143], v[156:159], v[0:15]
	s_waitcnt lgkmcnt(0)
	v_mfma_f32_32x32x16_bf16 v[80:95], v[128:131], v[194:197], v[80:95]
	s_and_b64 vcc, exec, s[50:51]
	v_mfma_f32_32x32x16_bf16 v[80:95], v[132:135], v[214:217], v[80:95]
	v_mfma_f32_32x32x16_bf16 v[80:95], v[136:139], v[220:223], v[80:95]
	v_mfma_f32_32x32x16_bf16 v[80:95], v[140:143], v[232:235], v[80:95]
	s_cbranch_vccnz .Lm1_ybar0
	s_waitcnt vmcnt(6) lgkmcnt(0)
	s_barrier
